# grid barrier: XCC release word no longer updated (nobody polls it); released workgroups poll the cross-XCC generation word
# baseline (speedup 1.0000x reference)
; DI unsigned xb_ld(unsigned* p) { return __hip_atomic_load(p, __ATOMIC_RELAXED, __HIP_MEMORY_SCOPE_AGENT); }
; DI unsigned xb_add(unsigned* p, unsigned v) { return __hip_atomic_fetch_add(p, v, __ATOMIC_RELAXED, __HIP_MEMORY_SCOPE_AGENT); }
; #define XB_SPIN(cond, bar) do { unsigned _sp = 0; while (cond) { __builtin_amdgcn_s_sleep(1); \
;     if ((++_sp & 255u) == 0u) { if (xb_ld(&(bar)[XB_TMO])) break; if (_sp > XB_SPIN_CAP) { atomicAdd(&(bar)[XB_TMO], 1u); break; } } } } while (0)
; DI void xcd_barrier(const XcdBarrier& b) {
;     ...
;       const unsigned og = xb_add(&bar[XB_TOP], 1u);
;       const unsigned tg = og / nx;
;       if (og + 1u == (tg + 1u) * nx) xb_add(&bar[XB_TOPGEN], 1u);
;       else XB_SPIN(xb_ld(&bar[XB_TOPGEN]) == tg, bar);
;       __builtin_amdgcn_fence(__ATOMIC_ACQUIRE, "agent");
;       xb_add(&bar[XB_XGEN(b.x)], 1u);
;       asm volatile("s_waitcnt vmcnt(0)" ::: "memory");
.LBB0_144:
	s_or_b64 exec, exec, s[6:7]
	s_mov_b64 s[6:7], exec
	v_mbcnt_lo_u32_b32 v0, s6, 0
	v_mbcnt_hi_u32_b32 v0, s7, v0
	v_cmp_eq_u32_e32 vcc, 0, v0
	s_waitcnt vmcnt(0)
	buffer_inv sc1
	s_and_saveexec_b64 s[8:9], vcc
	s_cbranch_execz .LBB0_146
	s_bcnt1_i32_b64 s6, s[6:7]
	v_mov_b32_e32 v0, s6
	v_mov_b32_e32 v1, 0x2000
.LBB0_146:
	s_or_b64 exec, exec, s[8:9]
	s_waitcnt vmcnt(0)

; DI unsigned xb_ld(unsigned* p) { return __hip_atomic_load(p, __ATOMIC_RELAXED, __HIP_MEMORY_SCOPE_AGENT); }
; DI unsigned xb_add(unsigned* p, unsigned v) { return __hip_atomic_fetch_add(p, v, __ATOMIC_RELAXED, __HIP_MEMORY_SCOPE_AGENT); }
; #define XB_SPIN(cond, bar) do { unsigned _sp = 0; while (cond) { __builtin_amdgcn_s_sleep(1); \
;     if ((++_sp & 255u) == 0u) { if (xb_ld(&(bar)[XB_TMO])) break; if (_sp > XB_SPIN_CAP) { atomicAdd(&(bar)[XB_TMO], 1u); break; } } } } while (0)
; DI void xcd_barrier(const XcdBarrier& b) {
;     ...
;       const unsigned og = xb_add(&bar[XB_TOP], 1u);
;       const unsigned tg = og / nx;
;       if (og + 1u == (tg + 1u) * nx) xb_add(&bar[XB_TOPGEN], 1u);
;       else XB_SPIN(xb_ld(&bar[XB_TOPGEN]) == tg, bar);
;       __builtin_amdgcn_fence(__ATOMIC_ACQUIRE, "agent");
;       xb_add(&bar[XB_XGEN(b.x)], 1u);
;       asm volatile("s_waitcnt vmcnt(0)" ::: "memory");
.LBB0_230:
	s_or_b64 exec, exec, s[6:7]
	s_mov_b64 s[6:7], exec
	v_mbcnt_lo_u32_b32 v0, s6, 0
	v_mbcnt_hi_u32_b32 v0, s7, v0
	v_cmp_eq_u32_e32 vcc, 0, v0
	s_waitcnt vmcnt(0)
	buffer_inv sc1
	s_and_saveexec_b64 s[10:11], vcc
	s_cbranch_execz .LBB0_232
	s_bcnt1_i32_b64 s2, s[6:7]
	v_mov_b32_e32 v0, s2
	v_mov_b32_e32 v1, 0x2000
.LBB0_232:
	s_or_b64 exec, exec, s[10:11]
	s_waitcnt vmcnt(0)

; DI unsigned xb_ld(unsigned* p) { return __hip_atomic_load(p, __ATOMIC_RELAXED, __HIP_MEMORY_SCOPE_AGENT); }
; DI unsigned xb_add(unsigned* p, unsigned v) { return __hip_atomic_fetch_add(p, v, __ATOMIC_RELAXED, __HIP_MEMORY_SCOPE_AGENT); }
; #define XB_SPIN(cond, bar) do { unsigned _sp = 0; while (cond) { __builtin_amdgcn_s_sleep(1); \
;     if ((++_sp & 255u) == 0u) { if (xb_ld(&(bar)[XB_TMO])) break; if (_sp > XB_SPIN_CAP) { atomicAdd(&(bar)[XB_TMO], 1u); break; } } } } while (0)
; DI void xcd_barrier(const XcdBarrier& b) {
;     ...
;       const unsigned og = xb_add(&bar[XB_TOP], 1u);
;       const unsigned tg = og / nx;
;       if (og + 1u == (tg + 1u) * nx) xb_add(&bar[XB_TOPGEN], 1u);
;       else XB_SPIN(xb_ld(&bar[XB_TOPGEN]) == tg, bar);
;       __builtin_amdgcn_fence(__ATOMIC_ACQUIRE, "agent");
;       xb_add(&bar[XB_XGEN(b.x)], 1u);
;       asm volatile("s_waitcnt vmcnt(0)" ::: "memory");
.LBB0_406:
	s_or_b64 exec, exec, s[6:7]
	s_mov_b64 s[6:7], exec
	v_mbcnt_lo_u32_b32 v0, s6, 0
	v_mbcnt_hi_u32_b32 v0, s7, v0
	v_cmp_eq_u32_e32 vcc, 0, v0
	s_waitcnt vmcnt(0)
	buffer_inv sc1
	s_and_saveexec_b64 s[8:9], vcc
	s_cbranch_execz .LBB0_408
	s_bcnt1_i32_b64 s2, s[6:7]
	v_mov_b32_e32 v0, s2
	v_mov_b32_e32 v1, 0x2000
.LBB0_408:
	s_or_b64 exec, exec, s[8:9]
	s_waitcnt vmcnt(0)

; DI unsigned xb_ld(unsigned* p) { return __hip_atomic_load(p, __ATOMIC_RELAXED, __HIP_MEMORY_SCOPE_AGENT); }
; DI unsigned xb_add(unsigned* p, unsigned v) { return __hip_atomic_fetch_add(p, v, __ATOMIC_RELAXED, __HIP_MEMORY_SCOPE_AGENT); }
; #define XB_SPIN(cond, bar) do { unsigned _sp = 0; while (cond) { __builtin_amdgcn_s_sleep(1); \
;     if ((++_sp & 255u) == 0u) { if (xb_ld(&(bar)[XB_TMO])) break; if (_sp > XB_SPIN_CAP) { atomicAdd(&(bar)[XB_TMO], 1u); break; } } } } while (0)
; DI void xcd_barrier(const XcdBarrier& b) {
;     ...
;       const unsigned og = xb_add(&bar[XB_TOP], 1u);
;       const unsigned tg = og / nx;
;       if (og + 1u == (tg + 1u) * nx) xb_add(&bar[XB_TOPGEN], 1u);
;       else XB_SPIN(xb_ld(&bar[XB_TOPGEN]) == tg, bar);
;       __builtin_amdgcn_fence(__ATOMIC_ACQUIRE, "agent");
;       xb_add(&bar[XB_XGEN(b.x)], 1u);
;       asm volatile("s_waitcnt vmcnt(0)" ::: "memory");
.LBB0_685:
	s_or_b64 exec, exec, s[6:7]
	s_mov_b64 s[6:7], exec
	v_mbcnt_lo_u32_b32 v0, s6, 0
	v_mbcnt_hi_u32_b32 v0, s7, v0
	v_cmp_eq_u32_e32 vcc, 0, v0
	s_waitcnt vmcnt(0)
	buffer_inv sc1
	s_and_saveexec_b64 s[8:9], vcc
	s_cbranch_execz .LBB0_687
	s_bcnt1_i32_b64 s2, s[6:7]
	v_mov_b32_e32 v0, s2
	v_mov_b32_e32 v1, 0x2000
.LBB0_687:
	s_or_b64 exec, exec, s[8:9]
	s_waitcnt vmcnt(0)

; DI unsigned xb_ld(unsigned* p) { return __hip_atomic_load(p, __ATOMIC_RELAXED, __HIP_MEMORY_SCOPE_AGENT); }
; DI unsigned xb_add(unsigned* p, unsigned v) { return __hip_atomic_fetch_add(p, v, __ATOMIC_RELAXED, __HIP_MEMORY_SCOPE_AGENT); }
; #define XB_SPIN(cond, bar) do { unsigned _sp = 0; while (cond) { __builtin_amdgcn_s_sleep(1); \
;     if ((++_sp & 255u) == 0u) { if (xb_ld(&(bar)[XB_TMO])) break; if (_sp > XB_SPIN_CAP) { atomicAdd(&(bar)[XB_TMO], 1u); break; } } } } while (0)
; DI void xcd_barrier(const XcdBarrier& b) {
;     ...
;       const unsigned og = xb_add(&bar[XB_TOP], 1u);
;       const unsigned tg = og / nx;
;       if (og + 1u == (tg + 1u) * nx) xb_add(&bar[XB_TOPGEN], 1u);
;       else XB_SPIN(xb_ld(&bar[XB_TOPGEN]) == tg, bar);
;       __builtin_amdgcn_fence(__ATOMIC_ACQUIRE, "agent");
;       xb_add(&bar[XB_XGEN(b.x)], 1u);
;       asm volatile("s_waitcnt vmcnt(0)" ::: "memory");
.LBB0_758:
	s_or_b64 exec, exec, s[6:7]
	s_mov_b64 s[6:7], exec
	v_mbcnt_lo_u32_b32 v0, s6, 0
	v_mbcnt_hi_u32_b32 v0, s7, v0
	v_cmp_eq_u32_e32 vcc, 0, v0
	s_waitcnt vmcnt(0)
	buffer_inv sc1
	s_and_saveexec_b64 s[8:9], vcc
	s_cbranch_execz .LBB0_149
	s_bcnt1_i32_b64 s2, s[6:7]
	v_mov_b32_e32 v0, s2
	v_mov_b32_e32 v1, 0x2000
	s_branch .LBB0_149
